# GEMM instance prologue de-serialised: second k-step's LDS-DMA loads issued before the first k-step's wait+barrier
# baseline (speedup 1.0000x reference)
; #define PG8_STAGE(bufoff, gbase, voff) do { _Pragma("unroll") for (int _i = 0; _i < 2; ++_i) \
;         __builtin_amdgcn_global_load_lds((const unsigned*)((const char*)(gbase) + (voff)[_i]), (LAS unsigned*)(lds + (bufoff) + ldsw + _i * 8192), 16, 0, 0); } while (0)
; #define PG8_WAIT_V(n) asm volatile("s_waitcnt vmcnt(" #n ")" ::: "memory")
; #define PG8_BAR __builtin_amdgcn_s_barrier()
; template <class Epi, bool ALIGN_EPI>
; __device__ __forceinline__ void gemm_phase(LAS unsigned char* lds, const Gemm g, const StaticOrder& S, const Epi& E, const int tid) {
;     ...
;     PG8_STAGE(PG8_SB(0, 0), cB, voffB); PG8_STAGE(PG8_SB(0, 1), cB + hB, voffB); PG8_STAGE(PG8_SA(0, 0), cA, voffA); PG8_STAGE(PG8_SA(0, 1), cA + hA, voffA);
;     if (wr == 1) PG8_BAR;
;     PG8_WAIT_V(2); PG8_BAR;
;     PG8_STAGE(PG8_SB(1, 0), cB + kstep, voffB); PG8_STAGE(PG8_SA(1, 0), cA + kstep, voffA); PG8_STAGE(PG8_SB(1, 1), cB + hB + kstep, voffB);
;     PG8_WAIT_V(6); PG8_BAR;
.LBB0_226:
	v_mov_b32_e32 v181, v169
	v_lshl_add_u64 v[4:5], s[46:47], 0, v[180:181]
	v_mov_b32_e32 v185, v169
	v_lshl_add_u64 v[6:7], s[46:47], 0, v[184:185]
	v_mov_b32_e32 v179, v169
	s_add_i32 m0, s53, 0x18000
	v_lshl_add_u64 v[4:5], v[4:5], 0, s[92:93]
	v_lshl_add_u64 v[12:13], v[128:129], 0, v[178:179]
	v_mov_b32_e32 v183, v169
	global_load_lds_dwordx4 v[4:5], off
	v_lshl_add_u64 v[4:5], v[6:7], 0, s[92:93]
	s_add_i32 m0, s53, 0x1a000
	s_add_i32 s57, s53, 0x8000
	v_lshl_add_u64 v[14:15], v[128:129], 0, v[182:183]
	global_load_lds_dwordx4 v[4:5], off
	v_lshl_add_u64 v[4:5], v[12:13], 0, s[92:93]
	s_mov_b32 m0, s57
	s_add_i32 s58, s53, 0xa000
	v_lshl_add_u64 v[8:9], s[10:11], 0, v[180:181]
	global_load_lds_dwordx4 v[4:5], off
	v_lshl_add_u64 v[4:5], v[14:15], 0, s[92:93]
	s_mov_b32 m0, s58
	v_lshl_add_u64 v[10:11], s[10:11], 0, v[184:185]
	global_load_lds_dwordx4 v[4:5], off
	s_add_i32 m0, s53, 0x1c000
	v_lshl_add_u64 v[4:5], v[8:9], 0, s[92:93]
	global_load_lds_dwordx4 v[4:5], off
	v_lshl_add_u64 v[4:5], v[10:11], 0, s[92:93]
	s_add_i32 m0, s53, 0x1e000
	s_lshl_b32 s59, s7, 3
	global_load_lds_dwordx4 v[4:5], off
	v_cvt_f32_u32_e32 v4, s59
	s_lshl_b32 s10, s12, 12
	s_and_b32 s10, s10, 0x3000
	v_or_b32_e32 v218, s10, v217
	v_rcp_iflag_f32_e32 v4, v4
	s_sub_i32 s10, 0, s59
	s_waitcnt vmcnt(8)
	s_barrier
	s_waitcnt vmcnt(6)
	v_add_u32_e32 v0, v2, v0
	v_mul_f32_e32 v4, 0x4f7ffffe, v4
	v_cvt_u32_f32_e32 v4, v4
	v_lshl_or_b32 v3, s13, 13, v217
	s_add_i32 s60, s48, -2
	s_ashr_i32 s61, s6, 31
	v_readfirstlane_b32 s11, v4
	v_add_u32_e32 v4, v216, v171
	s_mul_i32 s10, s10, s11
	v_add_lshl_u32 v168, v4, v173, 1
	s_mul_hi_u32 s10, s11, s10
	v_lshl_add_u64 v[160:161], s[94:95], 0, v[168:169]
	v_add_lshl_u32 v168, v0, v1, 1
	s_ashr_i32 s62, s0, 31
	s_mov_b32 s39, s95
	s_lshl_b32 s63, s7, 4
	s_mov_b32 s64, 0
	s_add_i32 s65, s11, s10
	v_lshl_add_u64 v[162:163], s[94:95], 0, v[168:169]
	v_add_u32_e32 v219, 0, v3
	s_barrier
	s_branch .LBB0_228

; #define PG8_STAGE(bufoff, gbase, voff) do { _Pragma("unroll") for (int _i = 0; _i < 2; ++_i) \
;         __builtin_amdgcn_global_load_lds((const unsigned*)((const char*)(gbase) + (voff)[_i]), (LAS unsigned*)(lds + (bufoff) + ldsw + _i * 8192), 16, 0, 0); } while (0)
; #define PG8_WAIT_V(n) asm volatile("s_waitcnt vmcnt(" #n ")" ::: "memory")
; #define PG8_BAR __builtin_amdgcn_s_barrier()
; template <class Epi, bool ALIGN_EPI>
; __device__ __forceinline__ void gemm_phase(LAS unsigned char* lds, const Gemm g, const StaticOrder& S, const Epi& E, const int tid) {
;     ...
;     PG8_STAGE(PG8_SB(0, 0), cB, voffB); PG8_STAGE(PG8_SB(0, 1), cB + hB, voffB); PG8_STAGE(PG8_SA(0, 0), cA, voffA); PG8_STAGE(PG8_SA(0, 1), cA + hA, voffA);
;     if (wr == 1) PG8_BAR;
;     PG8_WAIT_V(2); PG8_BAR;
;     PG8_STAGE(PG8_SB(1, 0), cB + kstep, voffB); PG8_STAGE(PG8_SA(1, 0), cA + kstep, voffA); PG8_STAGE(PG8_SB(1, 1), cB + hB + kstep, voffB);
;     PG8_WAIT_V(6); PG8_BAR;
.LBB0_264:
	v_mov_b32_e32 v181, v169
	v_lshl_add_u64 v[0:1], s[14:15], 0, v[180:181]
	v_mov_b32_e32 v185, v169
	v_lshl_add_u64 v[2:3], s[14:15], 0, v[184:185]
	v_mov_b32_e32 v179, v169
	s_add_i32 m0, s51, 0x18000
	v_lshl_add_u64 v[0:1], v[0:1], 0, s[92:93]
	v_lshl_add_u64 v[8:9], v[128:129], 0, v[178:179]
	v_mov_b32_e32 v183, v169
	global_load_lds_dwordx4 v[0:1], off
	v_lshl_add_u64 v[0:1], v[2:3], 0, s[92:93]
	s_add_i32 m0, s51, 0x1a000
	s_add_i32 s55, s51, 0x8000
	v_lshl_add_u64 v[10:11], v[128:129], 0, v[182:183]
	global_load_lds_dwordx4 v[0:1], off
	v_lshl_add_u64 v[0:1], v[8:9], 0, s[92:93]
	s_mov_b32 m0, s55
	s_add_i32 s56, s51, 0xa000
	v_lshl_add_u64 v[4:5], s[8:9], 0, v[180:181]
	global_load_lds_dwordx4 v[0:1], off
	v_lshl_add_u64 v[0:1], v[10:11], 0, s[92:93]
	s_mov_b32 m0, s56
	v_lshl_add_u64 v[6:7], s[8:9], 0, v[184:185]
	global_load_lds_dwordx4 v[0:1], off
	s_add_i32 m0, s51, 0x1c000
	v_lshl_add_u64 v[0:1], v[4:5], 0, s[92:93]
	global_load_lds_dwordx4 v[0:1], off
	v_lshl_add_u64 v[0:1], v[6:7], 0, s[92:93]
	s_add_i32 m0, s51, 0x1e000
	s_lshl_b32 s61, s7, 3
	global_load_lds_dwordx4 v[0:1], off
	v_cvt_f32_u32_e32 v0, s61
	s_lshl_b32 s8, s10, 12
	s_and_b32 s8, s8, 0x3000
	v_or_b32_e32 v239, s8, v217
	v_rcp_iflag_f32_e32 v0, v0
	s_sub_i32 s8, 0, s61
	s_waitcnt vmcnt(8)
	s_barrier
	s_waitcnt vmcnt(6)
	v_lshl_or_b32 v12, s11, 13, v217
	v_mul_f32_e32 v0, 0x4f7ffffe, v0
	v_cvt_u32_f32_e32 v0, v0
	s_add_i32 s57, s48, -2
	s_ashr_i32 s58, s6, 31
	s_ashr_i32 s59, s0, 31
	v_readfirstlane_b32 s9, v0
	s_mul_i32 s8, s8, s9
	v_add_u32_e32 v0, v216, v171
	s_mul_hi_u32 s8, s9, s8
	v_add_lshl_u32 v168, v0, v173, 1
	s_mov_b32 s39, s95
	s_lshl_b32 s60, s7, 4
	s_mov_b32 s62, 0
	s_add_i32 s63, s9, s8
	v_lshl_add_u64 v[186:187], s[94:95], 0, v[168:169]
	v_lshl_add_u64 v[188:189], s[94:95], 0, v[182:183]
	v_add_u32_e32 v171, 0, v12
	s_barrier
	s_branch .LBB0_266

; #define PG8_STAGE(bufoff, gbase, voff) do { _Pragma("unroll") for (int _i = 0; _i < 2; ++_i) \
;         __builtin_amdgcn_global_load_lds((const unsigned*)((const char*)(gbase) + (voff)[_i]), (LAS unsigned*)(lds + (bufoff) + ldsw + _i * 8192), 16, 0, 0); } while (0)
; #define PG8_WAIT_V(n) asm volatile("s_waitcnt vmcnt(" #n ")" ::: "memory")
; #define PG8_BAR __builtin_amdgcn_s_barrier()
; template <class Epi, bool ALIGN_EPI>
; __device__ __forceinline__ void gemm_phase(LAS unsigned char* lds, const Gemm g, const StaticOrder& S, const Epi& E, const int tid) {
;     ...
;     PG8_STAGE(PG8_SB(0, 0), cB, voffB); PG8_STAGE(PG8_SB(0, 1), cB + hB, voffB); PG8_STAGE(PG8_SA(0, 0), cA, voffA); PG8_STAGE(PG8_SA(0, 1), cA + hA, voffA);
;     if (wr == 1) PG8_BAR;
;     PG8_WAIT_V(2); PG8_BAR;
;     PG8_STAGE(PG8_SB(1, 0), cB + kstep, voffB); PG8_STAGE(PG8_SA(1, 0), cA + kstep, voffA); PG8_STAGE(PG8_SB(1, 1), cB + hB + kstep, voffB);
;     PG8_WAIT_V(6); PG8_BAR;
.LBB0_297:
	v_lshl_add_u64 v[8:9], v[144:145], 0, v[168:169]
	v_mov_b32_e32 v129, v169
	v_lshl_add_u64 v[10:11], v[144:145], 0, v[128:129]
	v_mov_b32_e32 v133, v169
	s_add_i32 m0, s51, 0x18000
	v_lshl_add_u64 v[8:9], v[8:9], 0, s[92:93]
	v_lshl_add_u64 v[14:15], v[142:143], 0, v[132:133]
	v_mov_b32_e32 v131, v169
	global_load_lds_dwordx4 v[8:9], off
	v_lshl_add_u64 v[8:9], v[10:11], 0, s[92:93]
	s_add_i32 m0, s51, 0x1a000
	s_add_i32 s56, s51, 0x8000
	v_lshl_add_u64 v[16:17], v[142:143], 0, v[130:131]
	global_load_lds_dwordx4 v[8:9], off
	v_lshl_add_u64 v[8:9], v[14:15], 0, s[92:93]
	s_mov_b32 m0, s56
	s_add_i32 s57, s51, 0xa000
	v_lshl_add_u64 v[12:13], v[0:1], 0, v[168:169]
	global_load_lds_dwordx4 v[8:9], off
	v_lshl_add_u64 v[8:9], v[16:17], 0, s[92:93]
	s_mov_b32 m0, s57
	v_lshl_add_u64 v[0:1], v[0:1], 0, v[128:129]
	global_load_lds_dwordx4 v[8:9], off
	s_add_i32 m0, s51, 0x1c000
	v_lshl_add_u64 v[8:9], v[12:13], 0, s[92:93]
	global_load_lds_dwordx4 v[8:9], off
	v_lshl_add_u64 v[0:1], v[0:1], 0, s[92:93]
	s_add_i32 m0, s51, 0x1e000
	v_and_b32_e32 v18, 15, v170
	global_load_lds_dwordx4 v[0:1], off
	v_add_u32_e32 v0, v7, v5
	s_lshr_b32 s55, s1, 6
	v_and_b32_e32 v19, 48, v170
	v_lshlrev_b32_e32 v18, 6, v18
	v_lshlrev_b32_e32 v21, 2, v170
	s_lshl_b32 s9, s9, 12
	v_add_lshl_u32 v0, v0, v6, 1
	v_mov_b32_e32 v1, v169
	v_or_b32_e32 v20, v18, v19
	s_lshl_b32 s10, s10, 13
	v_and_b32_e32 v21, 32, v21
	s_and_b32 s9, s9, 0x3000
	s_waitcnt vmcnt(8)
	s_barrier
	s_waitcnt vmcnt(6)
	s_add_i32 s58, s55, -2
	v_lshl_add_u64 v[134:135], s[94:95], 0, v[0:1]
	v_add_u32_e32 v0, v4, v2
	v_bitop3_b32 v18, v18, v21, v19 bitop3:0x36
	v_bitop3_b32 v19, s10, v20, v21 bitop3:0xf6
	s_cmpk_lt_u32 s8, 0x100
	v_add_lshl_u32 v0, v0, v3, 1
	v_or_b32_e32 v151, s9, v18
	s_cselect_b64 s[42:43], -1, 0
	s_ashr_i32 s59, s6, 31
	s_mov_b32 s39, s95
	v_lshl_add_u64 v[136:137], s[94:95], 0, v[0:1]
	s_mov_b32 s60, 0
	v_add_u32_e32 v153, 0, v19
	s_barrier
	v_mov_b32_e32 v254, -1
	s_mov_b32 s101, 0
	s_branch .LBB0_300

; #define PG8_STAGE(bufoff, gbase, voff) do { _Pragma("unroll") for (int _i = 0; _i < 2; ++_i) \
;         __builtin_amdgcn_global_load_lds((const unsigned*)((const char*)(gbase) + (voff)[_i]), (LAS unsigned*)(lds + (bufoff) + ldsw + _i * 8192), 16, 0, 0); } while (0)
; #define PG8_WAIT_V(n) asm volatile("s_waitcnt vmcnt(" #n ")" ::: "memory")
; #define PG8_BAR __builtin_amdgcn_s_barrier()
; template <class Epi, bool ALIGN_EPI>
; __device__ __forceinline__ void gemm_phase(LAS unsigned char* lds, const Gemm g, const StaticOrder& S, const Epi& E, const int tid) {
;     ...
;     PG8_STAGE(PG8_SB(0, 0), cB, voffB); PG8_STAGE(PG8_SB(0, 1), cB + hB, voffB); PG8_STAGE(PG8_SA(0, 0), cA, voffA); PG8_STAGE(PG8_SA(0, 1), cA + hA, voffA);
;     if (wr == 1) PG8_BAR;
;     PG8_WAIT_V(2); PG8_BAR;
;     PG8_STAGE(PG8_SB(1, 0), cB + kstep, voffB); PG8_STAGE(PG8_SA(1, 0), cA + kstep, voffA); PG8_STAGE(PG8_SB(1, 1), cB + hB + kstep, voffB);
;     PG8_WAIT_V(6); PG8_BAR;
.LBB0_320:
	v_lshl_add_u64 v[8:9], v[144:145], 0, v[168:169]
	v_mov_b32_e32 v129, v169
	v_lshl_add_u64 v[10:11], v[144:145], 0, v[128:129]
	v_mov_b32_e32 v133, v169
	s_add_i32 m0, s51, 0x18000
	v_lshl_add_u64 v[8:9], v[8:9], 0, s[92:93]
	v_lshl_add_u64 v[14:15], v[142:143], 0, v[132:133]
	v_mov_b32_e32 v131, v169
	global_load_lds_dwordx4 v[8:9], off
	v_lshl_add_u64 v[8:9], v[10:11], 0, s[92:93]
	s_add_i32 m0, s51, 0x1a000
	s_add_i32 s56, s51, 0x8000
	v_lshl_add_u64 v[16:17], v[142:143], 0, v[130:131]
	global_load_lds_dwordx4 v[8:9], off
	v_lshl_add_u64 v[8:9], v[14:15], 0, s[92:93]
	s_mov_b32 m0, s56
	s_add_i32 s57, s51, 0xa000
	v_lshl_add_u64 v[12:13], v[0:1], 0, v[168:169]
	global_load_lds_dwordx4 v[8:9], off
	v_lshl_add_u64 v[8:9], v[16:17], 0, s[92:93]
	s_mov_b32 m0, s57
	v_lshl_add_u64 v[0:1], v[0:1], 0, v[128:129]
	global_load_lds_dwordx4 v[8:9], off
	s_add_i32 m0, s51, 0x1c000
	v_lshl_add_u64 v[8:9], v[12:13], 0, s[92:93]
	global_load_lds_dwordx4 v[8:9], off
	v_lshl_add_u64 v[0:1], v[0:1], 0, s[92:93]
	s_add_i32 m0, s51, 0x1e000
	v_and_b32_e32 v18, 15, v170
	global_load_lds_dwordx4 v[0:1], off
	v_add_u32_e32 v0, v7, v5
	s_lshr_b32 s55, s1, 6
	v_and_b32_e32 v19, 48, v170
	v_lshlrev_b32_e32 v18, 6, v18
	v_lshlrev_b32_e32 v21, 2, v170
	s_lshl_b32 s9, s9, 12
	v_add_lshl_u32 v0, v0, v6, 1
	v_mov_b32_e32 v1, v169
	v_or_b32_e32 v20, v18, v19
	s_lshl_b32 s10, s10, 13
	v_and_b32_e32 v21, 32, v21
	s_and_b32 s9, s9, 0x3000
	s_waitcnt vmcnt(8)
	s_barrier
	s_waitcnt vmcnt(6)
	s_add_i32 s58, s55, -2
	v_lshl_add_u64 v[134:135], s[94:95], 0, v[0:1]
	v_add_u32_e32 v0, v4, v2
	v_bitop3_b32 v18, v18, v21, v19 bitop3:0x36
	v_bitop3_b32 v19, s10, v20, v21 bitop3:0xf6
	s_cmpk_lt_u32 s8, 0x100
	v_add_lshl_u32 v0, v0, v3, 1
	v_or_b32_e32 v153, s9, v18
	s_cselect_b64 s[42:43], -1, 0
	s_ashr_i32 s59, s6, 31
	s_mov_b32 s39, s95
	v_lshl_add_u64 v[136:137], s[94:95], 0, v[0:1]
	s_mov_b32 s60, 0
	v_add_u32_e32 v155, 0, v19
	s_barrier
	s_branch .LBB0_323

; #define PG8_STAGE(bufoff, gbase, voff) do { _Pragma("unroll") for (int _i = 0; _i < 2; ++_i) \
;         __builtin_amdgcn_global_load_lds((const unsigned*)((const char*)(gbase) + (voff)[_i]), (LAS unsigned*)(lds + (bufoff) + ldsw + _i * 8192), 16, 0, 0); } while (0)
; #define PG8_WAIT_V(n) asm volatile("s_waitcnt vmcnt(" #n ")" ::: "memory")
; #define PG8_BAR __builtin_amdgcn_s_barrier()
; template <class Epi, bool ALIGN_EPI>
; __device__ __forceinline__ void gemm_phase(LAS unsigned char* lds, const Gemm g, const StaticOrder& S, const Epi& E, const int tid) {
;     ...
;     PG8_STAGE(PG8_SB(0, 0), cB, voffB); PG8_STAGE(PG8_SB(0, 1), cB + hB, voffB); PG8_STAGE(PG8_SA(0, 0), cA, voffA); PG8_STAGE(PG8_SA(0, 1), cA + hA, voffA);
;     if (wr == 1) PG8_BAR;
;     PG8_WAIT_V(2); PG8_BAR;
;     PG8_STAGE(PG8_SB(1, 0), cB + kstep, voffB); PG8_STAGE(PG8_SA(1, 0), cA + kstep, voffA); PG8_STAGE(PG8_SB(1, 1), cB + hB + kstep, voffB);
;     PG8_WAIT_V(6); PG8_BAR;
.LBB0_343:
	v_lshl_add_u64 v[8:9], v[144:145], 0, v[168:169]
	v_mov_b32_e32 v129, v169
	v_lshl_add_u64 v[10:11], v[144:145], 0, v[128:129]
	v_mov_b32_e32 v133, v169
	s_add_i32 m0, s25, 0x18000
	v_lshl_add_u64 v[8:9], v[8:9], 0, s[92:93]
	v_lshl_add_u64 v[14:15], v[142:143], 0, v[132:133]
	v_mov_b32_e32 v131, v169
	global_load_lds_dwordx4 v[8:9], off
	v_lshl_add_u64 v[8:9], v[10:11], 0, s[92:93]
	s_add_i32 m0, s25, 0x1a000
	s_add_i32 s53, s25, 0x8000
	v_lshl_add_u64 v[16:17], v[142:143], 0, v[130:131]
	global_load_lds_dwordx4 v[8:9], off
	v_lshl_add_u64 v[8:9], v[14:15], 0, s[92:93]
	s_mov_b32 m0, s53
	s_add_i32 s54, s25, 0xa000
	v_lshl_add_u64 v[12:13], v[0:1], 0, v[168:169]
	global_load_lds_dwordx4 v[8:9], off
	v_lshl_add_u64 v[8:9], v[16:17], 0, s[92:93]
	s_mov_b32 m0, s54
	v_lshl_add_u64 v[0:1], v[0:1], 0, v[128:129]
	global_load_lds_dwordx4 v[8:9], off
	s_add_i32 m0, s25, 0x1c000
	v_lshl_add_u64 v[8:9], v[12:13], 0, s[92:93]
	global_load_lds_dwordx4 v[8:9], off
	v_lshl_add_u64 v[0:1], v[0:1], 0, s[92:93]
	s_add_i32 m0, s25, 0x1e000
	v_and_b32_e32 v18, 15, v170
	global_load_lds_dwordx4 v[0:1], off
	v_add_u32_e32 v0, v7, v5
	s_lshr_b32 s1, s1, 6
	v_and_b32_e32 v19, 48, v170
	v_lshlrev_b32_e32 v18, 6, v18
	v_lshlrev_b32_e32 v21, 2, v170
	s_lshl_b32 s9, s9, 12
	v_add_lshl_u32 v0, v0, v6, 1
	v_mov_b32_e32 v1, v169
	v_or_b32_e32 v20, v18, v19
	s_lshl_b32 s10, s10, 13
	v_and_b32_e32 v21, 32, v21
	s_and_b32 s9, s9, 0x3000
	s_waitcnt vmcnt(8)
	s_barrier
	s_waitcnt vmcnt(6)
	s_add_i32 s55, s1, -2
	v_lshl_add_u64 v[134:135], s[94:95], 0, v[0:1]
	v_add_u32_e32 v0, v4, v2
	v_bitop3_b32 v18, v18, v21, v19 bitop3:0x36
	v_bitop3_b32 v19, s10, v20, v21 bitop3:0xf6
	s_cmpk_lt_u32 s8, 0x100
	v_add_lshl_u32 v0, v0, v3, 1
	v_or_b32_e32 v149, s9, v18
	s_cselect_b64 s[42:43], -1, 0
	s_ashr_i32 s56, s6, 31
	s_mov_b32 s39, s95
	v_lshl_add_u64 v[136:137], s[94:95], 0, v[0:1]
	s_mov_b32 s57, 0
	v_add_u32_e32 v151, 0, v19
	s_barrier
	v_mov_b32_e32 v254, -1
	s_mov_b32 s101, 0
	s_branch .LBB0_346

; #define PG8_STAGE(bufoff, gbase, voff) do { _Pragma("unroll") for (int _i = 0; _i < 2; ++_i) \
;         __builtin_amdgcn_global_load_lds((const unsigned*)((const char*)(gbase) + (voff)[_i]), (LAS unsigned*)(lds + (bufoff) + ldsw + _i * 8192), 16, 0, 0); } while (0)
; #define PG8_WAIT_V(n) asm volatile("s_waitcnt vmcnt(" #n ")" ::: "memory")
; #define PG8_BAR __builtin_amdgcn_s_barrier()
; template <class Epi, bool ALIGN_EPI>
; __device__ __forceinline__ void gemm_phase(LAS unsigned char* lds, const Gemm g, const StaticOrder& S, const Epi& E, const int tid) {
;     ...
;     PG8_STAGE(PG8_SB(0, 0), cB, voffB); PG8_STAGE(PG8_SB(0, 1), cB + hB, voffB); PG8_STAGE(PG8_SA(0, 0), cA, voffA); PG8_STAGE(PG8_SA(0, 1), cA + hA, voffA);
;     if (wr == 1) PG8_BAR;
;     PG8_WAIT_V(2); PG8_BAR;
;     PG8_STAGE(PG8_SB(1, 0), cB + kstep, voffB); PG8_STAGE(PG8_SA(1, 0), cA + kstep, voffA); PG8_STAGE(PG8_SB(1, 1), cB + hB + kstep, voffB);
;     PG8_WAIT_V(6); PG8_BAR;
.LBB0_369:
	v_and_b32_e32 v8, 15, v170
	v_and_b32_e32 v9, 48, v170
	v_lshlrev_b32_e32 v8, 6, v8
	v_lshlrev_b32_e32 v11, 2, v170
	v_lshl_add_u64 v[0:1], s[30:31], 0, v[168:169]
	v_mov_b32_e32 v133, v169
	s_sext_i32_i8 s29, s8
	v_or_b32_e32 v10, v8, v9
	s_lshl_b32 s8, s13, 13
	v_and_b32_e32 v11, 32, v11
	v_lshl_add_u64 v[2:3], s[30:31], 0, v[132:133]
	v_mov_b32_e32 v129, v169
	v_bitop3_b32 v8, v8, v11, v9 bitop3:0x36
	v_bitop3_b32 v9, s8, v10, v11 bitop3:0xf6
	s_lshl_b32 s8, s9, 12
	s_add_i32 m0, s51, 0x18000
	v_lshl_add_u64 v[0:1], v[0:1], 0, s[92:93]
	v_lshl_add_u64 v[4:5], s[34:35], 0, v[128:129]
	v_mov_b32_e32 v131, v169
	s_and_b32 s8, s8, 0x3000
	global_load_lds_dwordx4 v[0:1], off
	v_lshl_add_u64 v[0:1], v[2:3], 0, s[92:93]
	s_add_i32 m0, s51, 0x1a000
	s_add_i32 s55, s51, 0x8000
	s_add_i32 s56, s51, 0xa000
	v_lshl_add_u64 v[6:7], s[34:35], 0, v[130:131]
	v_or_b32_e32 v141, s8, v8
	global_load_lds_dwordx4 v[0:1], off
	v_lshl_add_u64 v[0:1], v[4:5], 0, s[92:93]
	s_mov_b32 m0, s55
	s_add_u32 s8, s30, 0x10080
	global_load_lds_dwordx4 v[0:1], off
	v_lshl_add_u64 v[0:1], v[6:7], 0, s[92:93]
	s_mov_b32 m0, s56
	s_addc_u32 s9, s31, 0
	global_load_lds_dwordx4 v[0:1], off
	s_add_i32 m0, s51, 0x1c000
	v_lshl_add_u64 v[0:1], s[8:9], 0, v[168:169]
	global_load_lds_dwordx4 v[0:1], off
	v_lshl_add_u64 v[0:1], s[8:9], 0, v[132:133]
	s_add_i32 m0, s51, 0x1e000
	s_cmpk_lt_u32 s12, 0x100
	global_load_lds_dwordx4 v[0:1], off
	s_waitcnt vmcnt(8)
	s_barrier
	s_waitcnt vmcnt(6)
	s_cselect_b64 s[12:13], -1, 0
	s_ashr_i32 s57, s6, 31
	s_mov_b32 s58, 0
	v_add_u32_e32 v145, 0, v9
	s_barrier
	s_branch .LBB0_372
